# ffn_in GEMM tile order: XCD owns 17 row tiles, 8x8 patches (same order as the gate queues)
# baseline (speedup 1.0000x reference)
; __device__ __forceinline__ int tidx() { int t = threadIdx.x; asm volatile("" : "+v"(t)); return t; }
; template <int NT>
; __device__ __forceinline__ void gemm_tile(f32x4 (&acc)[4][NT], const bf16_t* A, int lda, const bf16_t* B, int ldb, int K, bf16_t* sm) {
;     const int tid_ = tidx();
;     bf16_t* sA = sm; bf16_t* sB = sm + 128 * LDT;
;     const int tid = tid_, lane = tid & 63, wid = tid >> 6, wr = wid >> 1, wc = wid & 1;
;     const int fr = lane & 15, fq = lane >> 4;
;     const int lrow = tid >> 3, lkc = tid & 7;
;     const bf16_t* ga = A + (size_t)lrow * lda + lkc * 8;
;     const bf16_t* gb = B + (size_t)lrow * ldb + lkc * 8;
;     int sbrow[NT];
; #pragma unroll
;     for (int i = 0; i < NT; ++i) { const int g = lrow + 32 * i, W_ = 16 * NT, rem = g % W_; sbrow[i] = (g / W_) * W_ + (rem % NT) * 16 + rem / NT; }
; __device__ __forceinline__ void phase_ffn_in(const bf16_t* xb, const bf16_t* W, bf16_t* H, bf16_t* sm) {
;     ...
;     for (int t = blockIdx.x; t < 136 * 32; t += gridDim.x) {
;         const int tm = t >> 5, tn = t & 31;
;         f32x4 acc[4][4]; zero_acc<4>(acc);
;         gemm_tile<4>(acc, xb + (size_t)tm * 128 * 1024, 1024, W + (size_t)tn * 128 * 1024, 1024, 1024, sm);
.LBB0_1479:
	v_mov_b32_e32 v38, v192
	s_lshr_b32 s2, s11, 9
	s_lshl_b32 s2, s2, 6
	s_bfe_u32 s12, s11, 0x60003
	s_add_i32 s2, s2, s12
	s_mul_i32 s12, s2, 0x1e2
	s_lshr_b32 s12, s12, 16
	s_mul_i32 s18, s12, 0x88
	s_sub_i32 s2, s2, s18
	s_and_b32 s18, s11, 7
	s_mul_i32 s18, s18, 17
	s_lshr_b32 s19, s2, 3
	s_add_i32 s18, s18, s19
	s_lshl_b32 s12, s12, 3
	s_and_b32 s2, s2, 7
	s_add_i32 s12, s12, s2
	v_ashrrev_i32_e32 v0, 31, v38
	v_ashrrev_i32_e32 v30, 3, v38
	v_lshrrev_b32_e32 v0, 26, v0
	v_add_u32_e32 v0, v30, v0
	v_lshrrev_b32_e32 v1, 6, v0
	v_mul_i32_i24_e32 v1, 64, v1
	v_sub_u32_e32 v1, v30, v1
	v_lshrrev_b16_sdwa v2, v196, sext(v1) dst_sel:DWORD dst_unused:UNUSED_PAD src0_sel:DWORD src1_sel:BYTE_0
	v_and_b32_e32 v2, 3, v2
	v_add_u16_e32 v2, v1, v2
	v_ashrrev_i16_sdwa v3, v197, sext(v2) dst_sel:DWORD dst_unused:UNUSED_PAD src0_sel:DWORD src1_sel:BYTE_0
	v_and_b32_e32 v2, 0xfc, v2
	v_sub_u16_e32 v1, v1, v2
	v_and_b32_e32 v0, 0x7ffffc0, v0
	v_lshlrev_b32_sdwa v1, v198, sext(v1) dst_sel:DWORD dst_unused:UNUSED_PAD src0_sel:DWORD src1_sel:BYTE_0
	v_bfe_i32 v2, v3, 0, 16
	v_add3_u32 v39, v0, v2, v1
	v_add_u32_e32 v0, 32, v30
	v_ashrrev_i32_e32 v1, 31, v0
	v_lshrrev_b32_e32 v1, 26, v1
	v_add_u32_e32 v1, v0, v1
	v_lshrrev_b32_e32 v2, 6, v1
	v_mul_i32_i24_e32 v2, 64, v2
	v_sub_u32_e32 v0, v0, v2
	v_lshrrev_b16_sdwa v2, v196, sext(v0) dst_sel:DWORD dst_unused:UNUSED_PAD src0_sel:DWORD src1_sel:BYTE_0
	v_and_b32_e32 v2, 3, v2
	v_add_u16_e32 v2, v0, v2
	v_ashrrev_i16_sdwa v3, v197, sext(v2) dst_sel:DWORD dst_unused:UNUSED_PAD src0_sel:DWORD src1_sel:BYTE_0
	v_and_b32_e32 v2, 0xfc, v2
	v_sub_u16_e32 v0, v0, v2
	v_and_b32_e32 v1, 0x7ffffc0, v1
	v_lshlrev_b32_sdwa v0, v198, sext(v0) dst_sel:DWORD dst_unused:UNUSED_PAD src0_sel:DWORD src1_sel:BYTE_0
	v_bfe_i32 v2, v3, 0, 16
	v_add3_u32 v40, v1, v2, v0
	v_add_u32_e32 v0, 64, v30
	v_ashrrev_i32_e32 v1, 31, v0
	v_lshrrev_b32_e32 v1, 26, v1
	v_add_u32_e32 v1, v0, v1
	v_lshrrev_b32_e32 v2, 6, v1
	v_mul_i32_i24_e32 v2, 64, v2
	v_sub_u32_e32 v0, v0, v2
	v_lshrrev_b16_sdwa v2, v196, sext(v0) dst_sel:DWORD dst_unused:UNUSED_PAD src0_sel:DWORD src1_sel:BYTE_0
	v_and_b32_e32 v2, 3, v2
	v_add_u16_e32 v2, v0, v2
	v_ashrrev_i16_sdwa v3, v197, sext(v2) dst_sel:DWORD dst_unused:UNUSED_PAD src0_sel:DWORD src1_sel:BYTE_0
	v_and_b32_e32 v2, 0xfc, v2
	v_sub_u16_e32 v0, v0, v2
	v_and_b32_e32 v1, 0x7ffffc0, v1
	v_lshlrev_b32_sdwa v0, v198, sext(v0) dst_sel:DWORD dst_unused:UNUSED_PAD src0_sel:DWORD src1_sel:BYTE_0
	v_bfe_i32 v2, v3, 0, 16
	s_waitcnt lgkmcnt(0)
	v_add3_u32 v41, v1, v2, v0
	v_add_u32_e32 v0, 0x60, v30
	v_ashrrev_i32_e32 v1, 31, v0
	v_lshrrev_b32_e32 v1, 26, v1
	v_add_u32_e32 v1, v0, v1
	v_lshrrev_b32_e32 v2, 6, v1
	v_mul_i32_i24_e32 v2, 64, v2
	v_sub_u32_e32 v0, v0, v2
	v_lshrrev_b16_sdwa v2, v196, sext(v0) dst_sel:DWORD dst_unused:UNUSED_PAD src0_sel:DWORD src1_sel:BYTE_0
	s_mov_b32 s2, s12
	s_ashr_i32 s19, s18, 31
	v_and_b32_e32 v2, 3, v2
	s_lshl_b32 s86, s2, 18
	s_lshl_b64 s[22:23], s[18:19], 18
	v_add_u16_e32 v2, v0, v2
	s_add_u32 s24, s80, s22
	v_ashrrev_i16_sdwa v3, v197, sext(v2) dst_sel:DWORD dst_unused:UNUSED_PAD src0_sel:DWORD src1_sel:BYTE_0
	v_and_b32_e32 v2, 0xfc, v2
	s_addc_u32 s25, s81, s23
	s_lshl_b32 s2, s12, 18
	v_sub_u16_e32 v0, v0, v2
	s_add_u32 s40, s16, s2
	v_and_b32_e32 v1, 0x7ffffc0, v1
	v_lshlrev_b32_sdwa v0, v198, sext(v0) dst_sel:DWORD dst_unused:UNUSED_PAD src0_sel:DWORD src1_sel:BYTE_0
	v_bfe_i32 v2, v3, 0, 16
	v_ashrrev_i32_e32 v31, 31, v30
	s_addc_u32 s41, s17, 0
	v_add3_u32 v42, v1, v2, v0
	v_lshlrev_b64 v[32:33], 11, v[30:31]
	v_lshlrev_b32_e32 v2, 4, v38
	v_lshl_add_u64 v[0:1], s[40:41], 0, v[32:33]
	v_and_b32_e32 v12, 0x70, v2
	v_lshl_add_u64 v[8:9], v[0:1], 0, v[12:13]
	v_add_co_u32_e32 v0, vcc, s7, v8
	v_lshl_add_u64 v[18:19], s[24:25], 0, v[32:33]
	s_nop 0
	v_addc_co_u32_e32 v1, vcc, 0, v9, vcc
	v_add_co_u32_e32 v10, vcc, s37, v8
	v_lshl_add_u64 v[26:27], v[18:19], 0, v[12:13]
	s_nop 0
	v_addc_co_u32_e32 v11, vcc, 0, v9, vcc
	v_add_co_u32_e32 v14, vcc, s73, v8
	v_mov_b32_e32 v250, v8
	v_mov_b32_e32 v251, v9
	s_nop 0
	v_addc_co_u32_e32 v15, vcc, 0, v9, vcc
	v_add_co_u32_e32 v18, vcc, s7, v26
	s_nop 0
	v_addc_co_u32_e32 v19, vcc, 0, v27, vcc
	v_add_co_u32_e32 v28, vcc, s37, v26
	v_mov_b32_e32 v248, v26
	v_mov_b32_e32 v249, v27
	s_nop 0
	v_addc_co_u32_e32 v29, vcc, 0, v27, vcc
	v_add_co_u32_e32 v34, vcc, s73, v26
	v_and_b32_e32 v31, 15, v38
	s_nop 0
	v_addc_co_u32_e32 v35, vcc, 0, v27, vcc
	s_nop 0
	v_lshrrev_b32_e32 v44, 1, v38
	v_and_or_b32 v31, v44, s3, v31
	v_mul_lo_u32 v44, v31, s89
	v_mul_lo_u32 v45, v30, s89
	v_lshl_add_u64 v[30:31], s[22:23], 0, v[32:33]
	v_or_b32_e32 v30, v30, v12
	v_lshl_add_u64 v[98:99], s[58:59], 0, v[30:31]
	v_lshl_add_u64 v[30:31], s[86:87], 0, v[32:33]
	v_and_b32_e32 v43, 48, v38
	v_and_b32_e32 v38, 0x4f, v38
	v_or_b32_e32 v30, v30, v12
	v_mul_u32_u24_e32 v38, 0xa0, v38
	v_mul_lo_u32 v39, v39, s89
	v_mul_lo_u32 v40, v40, s89
	v_mul_lo_u32 v41, v41, s89
	v_mul_lo_u32 v42, v42, s89
	v_lshl_add_u64 v[100:101], s[16:17], 0, v[30:31]
	v_mov_b32_e32 v30, 0
	s_mov_b64 s[22:23], 0
; template <int NT>
; __device__ __forceinline__ void gemm_tile(f32x4 (&acc)[4][NT], const bf16_t* A, int lda, const bf16_t* B, int ldb, int K, bf16_t* sm) {
;     ...
;     const bf16_t* ga = A + (size_t)lrow * lda + lkc * 8;
;     const bf16_t* gb = B + (size_t)lrow * ldb + lkc * 8;
;     int sbrow[NT];
; #pragma unroll
;     for (int i = 0; i < NT; ++i) { const int g = lrow + 32 * i, W_ = 16 * NT, rem = g % W_; sbrow[i] = (g / W_) * W_ + (rem % NT) * 16 + rem / NT; }
;     u32x4 ra0[4], rb0[NT];
; #pragma unroll
;     for (int i = 0; i < 4; ++i) ra0[i] = *(const u32x4*)(ga + (size_t)(32 * i) * lda);
; #pragma unroll
;     for (int i = 0; i < NT; ++i) rb0[i] = *(const u32x4*)(gb + (size_t)(32 * i) * ldb);
;     const int nk = K >> 6;
;     for (int kt = 0; kt < nk; ++kt) {
;         lds_barrier();
; #pragma unroll
;         for (int i = 0; i < 4; ++i) *(u32x4*)(sA + (lrow + 32 * i) * LDT + lkc * 8) = ra0[i];
; #pragma unroll
;         for (int i = 0; i < NT; ++i) *(u32x4*)(sB + sbrow[i] * LDT + lkc * 8) = rb0[i];
;         lds_barrier();
;         if (kt + 1 < nk) {
;             ga += 64; gb += 64;
; #pragma unroll
;             for (int i = 0; i < 4; ++i) ra0[i] = *(const u32x4*)(ga + (size_t)(32 * i) * lda);
; #pragma unroll
;             for (int i = 0; i < NT; ++i) rb0[i] = *(const u32x4*)(gb + (size_t)(32 * i) * ldb);
;         }
	v_add_u32_e32 v105, v12, v45
	v_add_u32_e32 v106, v12, v39
	v_add_u32_e32 v107, v12, v40
	v_add_u32_e32 v108, v12, v41
	v_add_u32_e32 v109, v12, v42
	v_add_u32_e32 v104, v43, v44
	v_add_u32_e32 v12, v43, v38
	v_mov_b32_e32 v31, v30
	v_mov_b32_e32 v32, v30
	v_mov_b32_e32 v33, v30
	v_mov_b32_e32 v38, v30
	v_mov_b32_e32 v39, v30
	v_mov_b32_e32 v40, v30
	v_mov_b32_e32 v41, v30
	v_mov_b32_e32 v42, v30
	v_mov_b32_e32 v43, v30
	v_mov_b32_e32 v44, v30
	v_mov_b32_e32 v45, v30
	v_mov_b32_e32 v46, v30
	v_mov_b32_e32 v47, v30
	v_mov_b32_e32 v48, v30
	v_mov_b32_e32 v49, v30
	v_mov_b32_e32 v50, v30
	v_mov_b32_e32 v51, v30
	v_mov_b32_e32 v52, v30
	v_mov_b32_e32 v53, v30
	v_mov_b32_e32 v54, v30
	v_mov_b32_e32 v55, v30
	v_mov_b32_e32 v56, v30
	v_mov_b32_e32 v57, v30
	v_mov_b32_e32 v58, v30
	v_mov_b32_e32 v59, v30
	v_mov_b32_e32 v60, v30
	v_mov_b32_e32 v61, v30
	v_mov_b32_e32 v62, v30
	v_mov_b32_e32 v63, v30
	v_mov_b32_e32 v64, v30
	v_mov_b32_e32 v65, v30
	v_mov_b32_e32 v66, v30
	v_mov_b32_e32 v67, v30
	v_mov_b32_e32 v68, v30
	v_mov_b32_e32 v69, v30
	v_mov_b32_e32 v70, v30
	v_mov_b32_e32 v71, v30
	v_mov_b32_e32 v72, v30
	v_mov_b32_e32 v73, v30
	v_mov_b32_e32 v74, v30
	v_mov_b32_e32 v75, v30
	v_mov_b32_e32 v76, v30
	v_mov_b32_e32 v77, v30
	v_mov_b32_e32 v78, v30
	v_mov_b32_e32 v79, v30
	v_mov_b32_e32 v80, v30
	v_mov_b32_e32 v81, v30
	v_mov_b32_e32 v82, v30
	v_mov_b32_e32 v83, v30
	v_mov_b32_e32 v84, v30
	v_mov_b32_e32 v85, v30
	v_mov_b32_e32 v86, v30
	v_mov_b32_e32 v87, v30
	v_mov_b32_e32 v88, v30
	v_mov_b32_e32 v89, v30
	v_mov_b32_e32 v90, v30
	v_mov_b32_e32 v91, v30
	v_mov_b32_e32 v92, v30
	v_mov_b32_e32 v93, v30
	v_mov_b32_e32 v94, v30
	v_mov_b32_e32 v95, v30
	v_mov_b32_e32 v96, v30
	v_mov_b32_e32 v97, v30
	v_writelane_b32 v234, s90, 0
	v_writelane_b32 v234, s91, 1
	v_writelane_b32 v234, s92, 2
	v_writelane_b32 v234, s93, 3
	v_writelane_b32 v234, s94, 4
	v_writelane_b32 v234, s95, 5
	v_bfe_u32 v160, v192, 3, 3
	v_and_b32_e32 v161, 7, v192
	v_xor_b32_e32 v161, v160, v161
	v_lshlrev_b32_e32 v161, 4, v161
	v_lshrrev_b32_e32 v162, 6, v192
	v_lshl_add_u32 v163, v162, 5, v160
	v_mul_u32_u24_e32 v163, 0x800, v163
	v_add_u32_e32 v236, v163, v161
	v_add_u32_e32 v237, 0x3c00, v236
	v_add_u32_e32 v238, 0x3c00, v237
	v_add_u32_e32 v239, 0x3c00, v238
	v_lshrrev_b32_e32 v163, 7, v192
	v_bfe_u32 v162, v192, 6, 1
	v_lshlrev_b32_e32 v163, 6, v163
	v_lshl_add_u32 v163, v160, 2, v163
	v_lshl_add_u32 v163, v162, 1, v163
	v_mul_u32_u24_e32 v163, 0x800, v163
	v_add_u32_e32 v240, v163, v161
	v_add_u32_e32 v241, 0xfc00, v240
	v_subrev_u32_e32 v242, 0xfc00, v241
	v_add_u32_e32 v243, 0xfc00, v242
	v_and_b32_e32 v160, 15, v192
	v_bfe_u32 v161, v192, 4, 2
	v_and_b32_e32 v162, 7, v160
	v_xor_b32_e32 v161, v161, v162
	v_lshlrev_b32_e32 v161, 4, v161
	v_lshl_add_u32 v161, v160, 7, v161
	v_lshrrev_b32_e32 v162, 7, v192
	v_lshl_add_u32 v244, v162, 13, v161
	v_bfe_u32 v162, v192, 6, 1
	v_lshl_add_u32 v246, v162, 13, v161
	v_add_u32_e32 v246, 0x4000, v246
	v_xor_b32_e32 v245, 64, v244
	v_xor_b32_e32 v247, 64, v246
	v_lshrrev_b32_e32 v160, 6, v192
	s_nop 0
	v_readfirstlane_b32 s94, v160
	v_readfirstlane_b32 s90, v248
	v_readfirstlane_b32 s91, v249
	v_readfirstlane_b32 s92, v250
	v_readfirstlane_b32 s93, v251
	s_mul_i32 s95, s94, 0x4000
	s_sub_u32 s90, s90, s95
	s_subb_u32 s91, s91, 0
	s_mul_i32 s95, s94, 0x4000
	s_sub_u32 s92, s92, s95
	s_subb_u32 s93, s93, 0
	s_lshl_b32 s94, s94, 10
	s_waitcnt lgkmcnt(0)
	s_barrier
	s_lshl_b32 s95, s94, 2
	s_add_u32 m0, s95, 0x0
	s_nop 0
	global_load_lds_dwordx4 v236, s[90:91]
	global_load_lds_dwordx4 v237, s[90:91] offset:1024
	global_load_lds_dwordx4 v238, s[90:91] offset:2048
	global_load_lds_dwordx4 v239, s[90:91] offset:3072
	s_mul_i32 s95, s94, 4
	s_add_u32 m0, s95, 0x4000
	s_nop 0
	global_load_lds_dwordx4 v240, s[92:93]
	global_load_lds_dwordx4 v241, s[92:93] offset:1024
	global_load_lds_dwordx4 v242, s[92:93] offset:2048
	global_load_lds_dwordx4 v243, s[92:93] offset:3072
	s_add_u32 s90, s90, 0x80
	s_addc_u32 s91, s91, 0
	s_add_u32 s92, s92, 0x80
	s_addc_u32 s93, s93, 0
	s_waitcnt vmcnt(0)
	s_barrier
	s_lshl_b32 s95, s94, 2
	s_add_u32 m0, s95, 0x8000
	s_nop 0
	global_load_lds_dwordx4 v236, s[90:91]
	global_load_lds_dwordx4 v237, s[90:91] offset:1024
	global_load_lds_dwordx4 v238, s[90:91] offset:2048
	global_load_lds_dwordx4 v239, s[90:91] offset:3072
	s_mul_i32 s95, s94, 4
	s_add_u32 m0, s95, 0xc000
	s_nop 0
	global_load_lds_dwordx4 v240, s[92:93]
	global_load_lds_dwordx4 v241, s[92:93] offset:1024
	global_load_lds_dwordx4 v242, s[92:93] offset:2048
	global_load_lds_dwordx4 v243, s[92:93] offset:3072
	s_add_u32 s90, s90, 0x80
	s_addc_u32 s91, s91, 0
	s_add_u32 s92, s92, 0x80
	s_addc_u32 s93, s93, 0
	ds_read_b128 v[110:113], v244 offset:0
	ds_read_b128 v[114:117], v244 offset:2048
	ds_read_b128 v[118:121], v244 offset:4096
	ds_read_b128 v[122:125], v244 offset:6144
	ds_read_b128 v[126:129], v246 offset:0
	ds_read_b128 v[130:133], v246 offset:2048
	ds_read_b128 v[134:137], v246 offset:4096
	ds_read_b128 v[138:141], v246 offset:6144
	s_movk_i32 s95, 0x6
	s_cmp_eq_u32 s95, 0
	s_cbranch_scc1 .Lgemm_x1480
